# forgetting-loop exit check: done-flag AND reduction done with v_bitop3 (AND3) - 4 ops instead of 7
# baseline (speedup 1.0000x reference)
; #define WAIT_OLD(S) do { if (TYPE == 2) asm volatile("s_waitcnt vmcnt(4)" : "+v"(rk0##S), "+v"(rk1##S), "+v"(rv0##S), "+v"(rv1##S), "+v"(rkr##S), "+v"(rck##S)); \
;         else asm volatile("s_waitcnt vmcnt(5)" : "+v"(rk0##S), "+v"(rk1##S), "+v"(rv0##S), "+v"(rv1##S), "+v"(rkr##S), "+v"(rck##S)); } while (0)
; #define SB_FLAGS(N_) do { if (TYPE != 1) { if (TYPE == 2) wdone = (__all(carry < -170.f) != 0); if (lane == 0) flags[((N_) & 1) * 8 + w8] = wdone ? 1u : 0u; } } while (0)
; template <int TYPE>
; DI void attn_item(KargPtr p, int b, int h, int qb, unsigned char* smem) {
;     ...
;         SB_FLAGS(n);
;         __syncthreads();
;         if (SB_DONE(n)) break;
;         if (n + 1 >= ntiles) break;
;         LOAD_TILE(A, TILE_OF(n + 3));
;         __builtin_amdgcn_sched_barrier(0);
;         compute(TILE_OF(n + 1), 1);
;         __builtin_amdgcn_sched_barrier(0);
;         WAIT_OLD(B);
;         STORE_TILE(B, 0);
;         SB_FLAGS(n + 1);
;         __syncthreads();
;         if (SB_DONE(n + 1)) break;
.LBB0_606:
	s_or_b64 exec, exec, s[10:11]
	v_mov_b32_e32 v0, s2
	s_waitcnt lgkmcnt(0)
	s_barrier
	ds_read_b128 v[48:51], v0
	v_mov_b32_e32 v1, s97
	ds_read_b128 v[226:229], v1
	s_waitcnt lgkmcnt(0)
	v_bitop3_b32 v0, v48, v49, v50 bitop3:0x80
	v_bitop3_b32 v0, v0, v51, v226 bitop3:0x80
	v_bitop3_b32 v0, v0, v227, v228 bitop3:0x80
	v_and_b32_e32 v0, v0, v229
	v_cmp_ne_u32_e32 vcc, 0, v0
	s_cbranch_vccz .LBB0_608
	s_cbranch_execz .LBB0_620
	s_branch .LBB0_564
